# activation tail folded into one fma with pre-halved gates; two unneeded wait states removed in the dot reduction
# speedup vs baseline: 1.0015x; 1.0015x over previous
.Lxp_sxqd:
	v_lshl_or_b32 v62, v59, 7, v60
	v_lshlrev_b32_e32 v63, 7, v89
	v_or3_b32 v63, v63, v60, 64
	s_nop 1
	v_mov_b32_dpp v64, v62 quad_perm:[1,0,3,2] row_mask:0xf bank_mask:0xf
	v_mov_b32_dpp v65, v63 quad_perm:[1,0,3,2] row_mask:0xf bank_mask:0xf
	s_mov_b32 vcc_lo, 0x99999999
	s_mov_b32 vcc_hi, 0x99999999
	v_min_u32_e32 v66, v62, v64
	v_max_u32_e32 v67, v62, v64
	v_min_u32_e32 v68, v63, v65
	v_max_u32_e32 v69, v63, v65
	v_cndmask_b32_e32 v62, v67, v66, vcc
	v_cndmask_b32_e32 v63, v69, v68, vcc
	s_nop 1
	v_mov_b32_dpp v64, v62 quad_perm:[2,3,0,1] row_mask:0xf bank_mask:0xf
	v_mov_b32_dpp v65, v63 quad_perm:[2,3,0,1] row_mask:0xf bank_mask:0xf
	s_mov_b32 vcc_lo, 0xc3c3c3c3
	s_mov_b32 vcc_hi, 0xc3c3c3c3
	v_min_u32_e32 v66, v62, v64
	v_max_u32_e32 v67, v62, v64
	v_min_u32_e32 v68, v63, v65
	v_max_u32_e32 v69, v63, v65
	v_cndmask_b32_e32 v62, v67, v66, vcc
	v_cndmask_b32_e32 v63, v69, v68, vcc
	s_nop 1
	v_mov_b32_dpp v64, v62 quad_perm:[1,0,3,2] row_mask:0xf bank_mask:0xf
	v_mov_b32_dpp v65, v63 quad_perm:[1,0,3,2] row_mask:0xf bank_mask:0xf
	s_mov_b32 vcc_lo, 0xa5a5a5a5
	s_mov_b32 vcc_hi, 0xa5a5a5a5
	v_min_u32_e32 v66, v62, v64
	v_max_u32_e32 v67, v62, v64
	v_min_u32_e32 v68, v63, v65
	v_max_u32_e32 v69, v63, v65
	v_cndmask_b32_e32 v62, v67, v66, vcc
	v_cndmask_b32_e32 v63, v69, v68, vcc
	ds_bpermute_b32 v64, v124, v62
	ds_bpermute_b32 v65, v124, v63
	s_mov_b32 vcc_lo, 0xf00ff00f
	s_mov_b32 vcc_hi, 0xf00ff00f
	s_waitcnt lgkmcnt(0)
	v_min_u32_e32 v66, v62, v64
	v_max_u32_e32 v67, v62, v64
	v_min_u32_e32 v68, v63, v65
	v_max_u32_e32 v69, v63, v65
	v_cndmask_b32_e32 v62, v67, v66, vcc
	v_cndmask_b32_e32 v63, v69, v68, vcc
	s_nop 1
	v_mov_b32_dpp v64, v62 quad_perm:[2,3,0,1] row_mask:0xf bank_mask:0xf
	v_mov_b32_dpp v65, v63 quad_perm:[2,3,0,1] row_mask:0xf bank_mask:0xf
	s_mov_b32 vcc_lo, 0xcc33cc33
	s_mov_b32 vcc_hi, 0xcc33cc33
	v_min_u32_e32 v66, v62, v64
	v_max_u32_e32 v67, v62, v64
	v_min_u32_e32 v68, v63, v65
	v_max_u32_e32 v69, v63, v65
	v_cndmask_b32_e32 v62, v67, v66, vcc
	v_cndmask_b32_e32 v63, v69, v68, vcc
	s_nop 1
	v_mov_b32_dpp v64, v62 quad_perm:[1,0,3,2] row_mask:0xf bank_mask:0xf
	v_mov_b32_dpp v65, v63 quad_perm:[1,0,3,2] row_mask:0xf bank_mask:0xf
	s_mov_b32 vcc_lo, 0xaa55aa55
	s_mov_b32 vcc_hi, 0xaa55aa55
	v_min_u32_e32 v66, v62, v64
	v_max_u32_e32 v67, v62, v64
	v_min_u32_e32 v68, v63, v65
	v_max_u32_e32 v69, v63, v65
	v_cndmask_b32_e32 v62, v67, v66, vcc
	v_cndmask_b32_e32 v63, v69, v68, vcc
	s_nop 1
	v_mov_b32_dpp v64, v62 row_ror:8 row_mask:0xf bank_mask:0xf
	v_mov_b32_dpp v65, v63 row_ror:8 row_mask:0xf bank_mask:0xf
	s_mov_b32 vcc_lo, 0xff0000ff
	s_mov_b32 vcc_hi, 0xff0000ff
	v_min_u32_e32 v66, v62, v64
	v_max_u32_e32 v67, v62, v64
	v_min_u32_e32 v68, v63, v65
	v_max_u32_e32 v69, v63, v65
	v_cndmask_b32_e32 v62, v67, v66, vcc
	v_cndmask_b32_e32 v63, v69, v68, vcc
	ds_bpermute_b32 v64, v124, v62
	ds_bpermute_b32 v65, v124, v63
	s_mov_b32 vcc_lo, 0xf0f00f0f
	s_mov_b32 vcc_hi, 0xf0f00f0f
	s_waitcnt lgkmcnt(0)
	v_min_u32_e32 v66, v62, v64
	v_max_u32_e32 v67, v62, v64
	v_min_u32_e32 v68, v63, v65
	v_max_u32_e32 v69, v63, v65
	v_cndmask_b32_e32 v62, v67, v66, vcc
	v_cndmask_b32_e32 v63, v69, v68, vcc
	s_nop 1
	v_mov_b32_dpp v64, v62 quad_perm:[2,3,0,1] row_mask:0xf bank_mask:0xf
	v_mov_b32_dpp v65, v63 quad_perm:[2,3,0,1] row_mask:0xf bank_mask:0xf
	s_mov_b32 vcc_lo, 0xcccc3333
	s_mov_b32 vcc_hi, 0xcccc3333
	v_min_u32_e32 v66, v62, v64
	v_max_u32_e32 v67, v62, v64
	v_min_u32_e32 v68, v63, v65
	v_max_u32_e32 v69, v63, v65
	v_cndmask_b32_e32 v62, v67, v66, vcc
	v_cndmask_b32_e32 v63, v69, v68, vcc
	s_nop 1
	v_mov_b32_dpp v64, v62 quad_perm:[1,0,3,2] row_mask:0xf bank_mask:0xf
	v_mov_b32_dpp v65, v63 quad_perm:[1,0,3,2] row_mask:0xf bank_mask:0xf
	s_mov_b32 vcc_lo, 0xaaaa5555
	s_mov_b32 vcc_hi, 0xaaaa5555
	v_min_u32_e32 v66, v62, v64
	v_max_u32_e32 v67, v62, v64
	v_min_u32_e32 v68, v63, v65
	v_max_u32_e32 v69, v63, v65
	v_cndmask_b32_e32 v62, v67, v66, vcc
	v_cndmask_b32_e32 v63, v69, v68, vcc
	ds_bpermute_b32 v64, v126, v62
	ds_bpermute_b32 v65, v126, v63
	s_mov_b32 vcc_lo, 0x0000ffff
	s_mov_b32 vcc_hi, 0xffff0000
	s_waitcnt lgkmcnt(0)
	v_min_u32_e32 v66, v62, v64
	v_max_u32_e32 v67, v62, v64
	v_min_u32_e32 v68, v63, v65
	v_max_u32_e32 v69, v63, v65
	v_cndmask_b32_e32 v62, v67, v66, vcc
	v_cndmask_b32_e32 v63, v69, v68, vcc
	s_nop 1
	v_mov_b32_dpp v64, v62 row_ror:8 row_mask:0xf bank_mask:0xf
	v_mov_b32_dpp v65, v63 row_ror:8 row_mask:0xf bank_mask:0xf
	s_mov_b32 vcc_lo, 0x00ff00ff
	s_mov_b32 vcc_hi, 0xff00ff00
	v_min_u32_e32 v66, v62, v64
	v_max_u32_e32 v67, v62, v64
	v_min_u32_e32 v68, v63, v65
	v_max_u32_e32 v69, v63, v65
	v_cndmask_b32_e32 v62, v67, v66, vcc
	v_cndmask_b32_e32 v63, v69, v68, vcc
	ds_bpermute_b32 v64, v124, v62
	ds_bpermute_b32 v65, v124, v63
	s_mov_b32 vcc_lo, 0x0f0f0f0f
	s_mov_b32 vcc_hi, 0xf0f0f0f0
	s_waitcnt lgkmcnt(0)
	v_min_u32_e32 v66, v62, v64
	v_max_u32_e32 v67, v62, v64
	v_min_u32_e32 v68, v63, v65
	v_max_u32_e32 v69, v63, v65
	v_cndmask_b32_e32 v62, v67, v66, vcc
	v_cndmask_b32_e32 v63, v69, v68, vcc
	s_nop 1
	v_mov_b32_dpp v64, v62 quad_perm:[2,3,0,1] row_mask:0xf bank_mask:0xf
	v_mov_b32_dpp v65, v63 quad_perm:[2,3,0,1] row_mask:0xf bank_mask:0xf
	s_mov_b32 vcc_lo, 0x33333333
	s_mov_b32 vcc_hi, 0xcccccccc
	v_min_u32_e32 v66, v62, v64
	v_max_u32_e32 v67, v62, v64
	v_min_u32_e32 v68, v63, v65
	v_max_u32_e32 v69, v63, v65
	v_cndmask_b32_e32 v62, v67, v66, vcc
	v_cndmask_b32_e32 v63, v69, v68, vcc
	s_nop 1
	v_mov_b32_dpp v64, v62 quad_perm:[1,0,3,2] row_mask:0xf bank_mask:0xf
	v_mov_b32_dpp v65, v63 quad_perm:[1,0,3,2] row_mask:0xf bank_mask:0xf
	s_mov_b32 vcc_lo, 0x55555555
	s_mov_b32 vcc_hi, 0xaaaaaaaa
	v_min_u32_e32 v66, v62, v64
	v_max_u32_e32 v67, v62, v64
	v_min_u32_e32 v68, v63, v65
	v_max_u32_e32 v69, v63, v65
	v_cndmask_b32_e32 v62, v67, v66, vcc
	v_cndmask_b32_e32 v63, v69, v68, vcc
	ds_bpermute_b32 v64, v127, v62
	ds_bpermute_b32 v65, v127, v63
	s_mov_b32 vcc_lo, 0xffffffff
	s_mov_b32 vcc_hi, 0x00000000
	s_waitcnt lgkmcnt(0)
	v_min_u32_e32 v66, v62, v64
	v_max_u32_e32 v67, v62, v64
	v_min_u32_e32 v68, v63, v65
	v_max_u32_e32 v69, v63, v65
	v_cndmask_b32_e32 v62, v67, v66, vcc
	v_cndmask_b32_e32 v63, v68, v69, vcc
	ds_bpermute_b32 v64, v126, v62
	ds_bpermute_b32 v65, v126, v63
	s_mov_b32 vcc_lo, 0x0000ffff
	s_mov_b32 vcc_hi, 0x0000ffff
	s_waitcnt lgkmcnt(0)
	v_min_u32_e32 v66, v62, v64
	v_max_u32_e32 v67, v62, v64
	v_min_u32_e32 v68, v63, v65
	v_max_u32_e32 v69, v63, v65
	v_cndmask_b32_e32 v62, v67, v66, vcc
	v_cndmask_b32_e32 v63, v68, v69, vcc
	s_nop 1
	v_mov_b32_dpp v64, v62 row_ror:8 row_mask:0xf bank_mask:0xf
	v_mov_b32_dpp v65, v63 row_ror:8 row_mask:0xf bank_mask:0xf
	s_mov_b32 vcc_lo, 0x00ff00ff
	s_mov_b32 vcc_hi, 0x00ff00ff
	v_min_u32_e32 v66, v62, v64
	v_max_u32_e32 v67, v62, v64
	v_min_u32_e32 v68, v63, v65
	v_max_u32_e32 v69, v63, v65
	v_cndmask_b32_e32 v62, v67, v66, vcc
	v_cndmask_b32_e32 v63, v68, v69, vcc
	ds_bpermute_b32 v64, v124, v62
	ds_bpermute_b32 v65, v124, v63
	s_mov_b32 vcc_lo, 0x0f0f0f0f
	s_mov_b32 vcc_hi, 0x0f0f0f0f
	s_waitcnt lgkmcnt(0)
	v_min_u32_e32 v66, v62, v64
	v_max_u32_e32 v67, v62, v64
	v_min_u32_e32 v68, v63, v65
	v_max_u32_e32 v69, v63, v65
	v_cndmask_b32_e32 v62, v67, v66, vcc
	v_cndmask_b32_e32 v63, v68, v69, vcc
	s_nop 1
	v_mov_b32_dpp v64, v62 quad_perm:[2,3,0,1] row_mask:0xf bank_mask:0xf
	v_mov_b32_dpp v65, v63 quad_perm:[2,3,0,1] row_mask:0xf bank_mask:0xf
	s_mov_b32 vcc_lo, 0x33333333
	s_mov_b32 vcc_hi, 0x33333333
	v_min_u32_e32 v66, v62, v64
	v_max_u32_e32 v67, v62, v64
	v_min_u32_e32 v68, v63, v65
	v_max_u32_e32 v69, v63, v65
	v_cndmask_b32_e32 v62, v67, v66, vcc
	v_cndmask_b32_e32 v63, v68, v69, vcc
	s_nop 1
	v_mov_b32_dpp v64, v62 quad_perm:[1,0,3,2] row_mask:0xf bank_mask:0xf
	v_mov_b32_dpp v65, v63 quad_perm:[1,0,3,2] row_mask:0xf bank_mask:0xf
	s_mov_b32 vcc_lo, 0x55555555
	s_mov_b32 vcc_hi, 0x55555555
	v_min_u32_e32 v66, v62, v64
	v_max_u32_e32 v67, v62, v64
	v_min_u32_e32 v68, v63, v65
	v_max_u32_e32 v69, v63, v65
	v_cndmask_b32_e32 v62, v67, v66, vcc
	v_cndmask_b32_e32 v63, v68, v69, vcc
	v_min_u32_e32 v66, v62, v63
	v_max_u32_e32 v63, v62, v63
	v_mov_b32_e32 v62, v66
	ds_bpermute_b32 v64, v127, v62
	ds_bpermute_b32 v65, v127, v63
	s_mov_b32 vcc_lo, 0xffffffff
	s_mov_b32 vcc_hi, 0x00000000
	s_waitcnt lgkmcnt(0)
	v_min_u32_e32 v66, v62, v64
	v_max_u32_e32 v67, v62, v64
	v_min_u32_e32 v68, v63, v65
	v_max_u32_e32 v69, v63, v65
	v_cndmask_b32_e32 v62, v67, v66, vcc
	v_cndmask_b32_e32 v63, v69, v68, vcc
	ds_bpermute_b32 v64, v126, v62
	ds_bpermute_b32 v65, v126, v63
	s_mov_b32 vcc_lo, 0x0000ffff
	s_mov_b32 vcc_hi, 0x0000ffff
	s_waitcnt lgkmcnt(0)
	v_min_u32_e32 v66, v62, v64
	v_max_u32_e32 v67, v62, v64
	v_min_u32_e32 v68, v63, v65
	v_max_u32_e32 v69, v63, v65
	v_cndmask_b32_e32 v62, v67, v66, vcc
	v_cndmask_b32_e32 v63, v69, v68, vcc
	s_nop 1
	v_mov_b32_dpp v64, v62 row_ror:8 row_mask:0xf bank_mask:0xf
	v_mov_b32_dpp v65, v63 row_ror:8 row_mask:0xf bank_mask:0xf
	s_mov_b32 vcc_lo, 0x00ff00ff
	s_mov_b32 vcc_hi, 0x00ff00ff
	v_min_u32_e32 v66, v62, v64
	v_max_u32_e32 v67, v62, v64
	v_min_u32_e32 v68, v63, v65
	v_max_u32_e32 v69, v63, v65
	v_cndmask_b32_e32 v62, v67, v66, vcc
	v_cndmask_b32_e32 v63, v69, v68, vcc
	ds_bpermute_b32 v64, v124, v62
	ds_bpermute_b32 v65, v124, v63
	s_mov_b32 vcc_lo, 0x0f0f0f0f
	s_mov_b32 vcc_hi, 0x0f0f0f0f
	s_waitcnt lgkmcnt(0)
	v_min_u32_e32 v66, v62, v64
	v_max_u32_e32 v67, v62, v64
	v_min_u32_e32 v68, v63, v65
	v_max_u32_e32 v69, v63, v65
	v_cndmask_b32_e32 v62, v67, v66, vcc
	v_cndmask_b32_e32 v63, v69, v68, vcc
	s_nop 1
	v_mov_b32_dpp v64, v62 quad_perm:[2,3,0,1] row_mask:0xf bank_mask:0xf
	v_mov_b32_dpp v65, v63 quad_perm:[2,3,0,1] row_mask:0xf bank_mask:0xf
	s_mov_b32 vcc_lo, 0x33333333
	s_mov_b32 vcc_hi, 0x33333333
	v_min_u32_e32 v66, v62, v64
	v_max_u32_e32 v67, v62, v64
	v_min_u32_e32 v68, v63, v65
	v_max_u32_e32 v69, v63, v65
	v_cndmask_b32_e32 v62, v67, v66, vcc
	v_cndmask_b32_e32 v63, v69, v68, vcc
	s_nop 1
	v_mov_b32_dpp v64, v62 quad_perm:[1,0,3,2] row_mask:0xf bank_mask:0xf
	v_mov_b32_dpp v65, v63 quad_perm:[1,0,3,2] row_mask:0xf bank_mask:0xf
	s_mov_b32 vcc_lo, 0x55555555
	s_mov_b32 vcc_hi, 0x55555555
	v_min_u32_e32 v66, v62, v64
	v_max_u32_e32 v67, v62, v64
	v_min_u32_e32 v68, v63, v65
	v_max_u32_e32 v69, v63, v65
	v_cndmask_b32_e32 v62, v67, v66, vcc
	v_cndmask_b32_e32 v63, v69, v68, vcc
	v_lshrrev_b32_e32 v250, 7, v62
	v_lshrrev_b32_e32 v88, 7, v63
	v_and_b32_e32 v64, 63, v62
	v_lshlrev_b32_e32 v64, 2, v64
	v_and_b32_e32 v65, 63, v63
	v_lshlrev_b32_e32 v65, 2, v65
	ds_bpermute_b32 v66, v64, v128
	ds_bpermute_b32 v67, v64, v129
	ds_bpermute_b32 v68, v65, v128
	ds_bpermute_b32 v69, v65, v129
	v_and_b32_e32 v70, 64, v62
	v_and_b32_e32 v71, 64, v63
	s_waitcnt lgkmcnt(0)
	v_cmp_eq_u32_e32 vcc, 0, v70
	s_nop 1
	v_cndmask_b32_e32 v251, v67, v66, vcc
	v_cmp_eq_u32_e32 vcc, 0, v71
	s_nop 1
	v_cndmask_b32_e32 v89, v69, v68, vcc
	v_mul_f32_e32 v251, 0.5, v251
	v_mul_f32_e32 v89, 0.5, v89
	s_add_i32 s2, s32, s25
	s_lshl_b32 s2, s2, 11
	v_lshl_add_u32 v249, v60, 3, s2
	global_store_dwordx2 v249, v[250:251], s[92:93]
	global_store_dwordx2 v249, v[88:89], s[92:93] offset:512
	v_and_b32_e32 v252, 15, v60
	v_lshlrev_b32_e32 v252, 4, v252
	ds_bpermute_b32 v64, v252, v250
	ds_bpermute_b32 v65, v252, v88
	s_mov_b32 vcc_lo, 0xffff0000
	s_mov_b32 vcc_hi, 0xffff0000
	s_waitcnt lgkmcnt(0)
	v_cndmask_b32_e32 v64, v64, v65, vcc
	v_and_b32_e32 v65, 31, v60
	s_lshl_b32 s2, s25, 5
	v_or_b32_e32 v65, s2, v65
	v_lshl_or_b32 v64, v64, 7, v65
	s_cmp_eq_u32 s25, 0
	s_cbranch_scc1 .Lxp_uk0
	s_cmp_eq_u32 s25, 1
	s_cbranch_scc1 .Lxp_uk1
	s_cmp_eq_u32 s25, 2
	s_cbranch_scc1 .Lxp_uk2
	s_mov_b32 vcc_lo, 0
	s_mov_b32 vcc_hi, -1
	s_nop 0
	v_cndmask_b32_e32 v241, v241, v64, vcc
	s_branch .Lxp_ukd

.Lxp_syncda:
	s_and_b32 s84, s84, 0x3fff
	s_lshl_b32 s2, s84, 11
	s_add_u32 s2, s18, s2
	s_addc_u32 s3, s19, 0
	global_load_dwordx4 v[72:75], v252, s[2:3]
	global_load_dwordx4 v[64:67], v252, s[2:3] offset:1024
	s_lshl_b32 s2, s84, 2
	v_writelane_b32 v147, s2, 0
	v_writelane_b32 v2, s85, 0
	s_and_b32 s86, s86, 0x3fff
	s_lshl_b32 s2, s86, 11
	s_add_u32 s2, s18, s2
	s_addc_u32 s3, s19, 0
	global_load_dwordx4 v[76:79], v252, s[2:3]
	global_load_dwordx4 v[68:71], v252, s[2:3] offset:1024
	s_lshl_b32 s2, s86, 2
	v_writelane_b32 v147, s2, 1
	v_writelane_b32 v2, s87, 1
	s_and_b32 s88, s88, 0x3fff
	s_lshl_b32 s2, s88, 11
	s_add_u32 s2, s18, s2
	s_addc_u32 s3, s19, 0
	global_load_dwordx4 v[80:83], v252, s[2:3]
	global_load_dwordx4 v[4:7], v252, s[2:3] offset:1024
	s_lshl_b32 s2, s88, 2
	v_writelane_b32 v147, s2, 2
	v_writelane_b32 v2, s89, 2
	s_and_b32 s90, s90, 0x3fff
	s_lshl_b32 s2, s90, 11
	s_add_u32 s2, s18, s2
	s_addc_u32 s3, s19, 0
	global_load_dwordx4 v[84:87], v252, s[2:3]
	global_load_dwordx4 v[128:131], v252, s[2:3] offset:1024
	s_lshl_b32 s2, s90, 2
	v_writelane_b32 v147, s2, 3
	v_writelane_b32 v2, s91, 3
	global_load_dword v88, v147, s[44:45]
	global_load_dword v89, v147, s[46:47]
	v_dot4_i32_i8 v149, v8, v133, 0
	v_dot4_i32_i8 v150, v16, v133, 0
	v_dot4_i32_i8 v151, v32, v133, 0
	v_dot4_i32_i8 v148, v36, v133, 0
	s_nop 0
	v_dot4c_i32_i8_e32 v149, v9, v134
	v_dot4c_i32_i8_e32 v150, v17, v134
	v_dot4c_i32_i8_e32 v151, v33, v134
	v_dot4c_i32_i8_e32 v148, v37, v134
	v_dot4c_i32_i8_e32 v149, v10, v135
	v_dot4c_i32_i8_e32 v150, v18, v135
	v_dot4c_i32_i8_e32 v151, v34, v135
	v_dot4c_i32_i8_e32 v148, v38, v135
	v_dot4c_i32_i8_e32 v149, v11, v136
	v_dot4c_i32_i8_e32 v150, v19, v136
	v_dot4c_i32_i8_e32 v151, v35, v136
	v_dot4c_i32_i8_e32 v148, v39, v136
	s_add_i32 s3, s25, 3
	s_min_u32 s3, s3, 0x7f
	s_cmp_lt_u32 s3, 64
	s_cselect_b64 vcc, -1, 0
	s_nop 0
	v_cndmask_b32_e32 v249, v241, v240, vcc
	s_nop 1
	v_readlane_b32 s2, v249, s3
	s_and_b32 s3, s2, 31
	s_lshl_b32 s3, s3, 5
	s_bfe_u32 s94, s2, 0x20005
	s_lshl_b32 s2, s94, 11
	s_add_i32 s3, s3, s2
	s_load_dwordx8 s[84:91], s[36:37], s3
	v_cndmask_b32_e64 v143, v149, v150, s[0:1]
	v_cndmask_b32_e64 v144, v150, v149, s[0:1]
	v_cndmask_b32_e64 v145, v151, v148, s[0:1]
	v_cndmask_b32_e64 v146, v148, v151, s[0:1]
	s_nop 1
	v_add_u32_dpp v144, v143, v144 quad_perm:[1,0,3,2] row_mask:0xf bank_mask:0xf
	v_add_u32_dpp v146, v145, v146 quad_perm:[1,0,3,2] row_mask:0xf bank_mask:0xf
	v_cndmask_b32_e64 v143, v144, v146, s[6:7]
	v_cndmask_b32_e64 v145, v146, v144, s[6:7]
	s_nop 1
	v_add_u32_dpp v145, v143, v145 quad_perm:[2,3,0,1] row_mask:0xf bank_mask:0xf
	s_nop 1
	v_add_u32_dpp v145, v145, v145 row_ror:4 row_mask:0xf bank_mask:0xf
	s_nop 1
	v_add_u32_dpp v145, v145, v145 row_ror:8 row_mask:0xf bank_mask:0xf
	ds_bpermute_b32 v143, v126, v145
	s_waitcnt lgkmcnt(0)
	v_add_u32_e32 v145, v145, v143
	ds_bpermute_b32 v143, v127, v145
	s_waitcnt lgkmcnt(0)
	v_add_u32_e32 v145, v145, v143
	v_cvt_f32_i32_e32 v56, v145
	v_mul_f32_e32 v59, v138, v56
	v_mul_f32_e32 v59, v137, v59
	v_mul_f32_e32 v56, 0x3f3504f3, v59
	v_fma_f32 v143, |v56|, s66, v120
	v_fma_f32 v143, |v56|, v143, s67
	v_fma_f32 v143, |v56|, v143, s68
	v_fma_f32 v143, |v56|, v143, s69
	v_fma_f32 v143, |v56|, v143, s70
	v_fma_f32 v143, |v56|, v143, s71
	v_fma_f32 v143, |v56|, v143, |v56|
	v_mul_f32_e32 v144, 0xbfb8aa3b, v143
	v_fma_f32 v146, v143, s72, -v144
	v_rndne_f32_e32 v3, v144
	v_fmac_f32_e32 v146, 0xb2a5705f, v143
	v_sub_f32_e32 v144, v144, v3
	v_add_f32_e32 v144, v144, v146
	v_cvt_i32_f32_e32 v146, v3
	v_exp_f32_e32 v144, v144
	v_cmp_nlt_f32_e32 vcc, s73, v143
	v_ldexp_f32 v144, v144, v146
	s_nop 0
	v_cndmask_b32_e32 v144, 0, v144, vcc
	v_cmp_ngt_f32_e32 vcc, s74, v143
	s_nop 1
	v_cndmask_b32_e32 v143, v121, v144, vcc
	v_sub_f32_e32 v143, 1.0, v143
	v_mul_f32_e32 v168, v56, v56
	v_fmamk_f32 v169, v168, 0xba1345e1, v117
	v_fmaak_f32 v169, v168, v169, 0xbcdac9b8
	v_fmaak_f32 v169, v168, v169, 0x3de703be
	v_fmaak_f32 v169, v168, v169, 0xbec09330
	v_fmaak_f32 v168, v168, v169, 0x3e0375d0
	v_fma_f32 v168, |v56|, v168, |v56|
	v_cmp_nlt_f32_e64 vcc, |v56|, 1.0
	s_nop 1
	v_cndmask_b32_e32 v143, v168, v143, vcc
	v_bfi_b32 v146, s75, v143, v56
	v_fma_f32 v145, v59, v146, v59
	v_mul_f32_e32 v144, v0, v145
	v_mul_f32_e32 v143, v139, v144
	s_nop 1
	v_readlane_b32 s40, v143, 0
	v_readlane_b32 s38, v143, 1
	v_readlane_b32 s42, v143, 2
	v_readlane_b32 s2, v143, 3
	s_nop 1
	v_add_f32_e32 v142, s40, v142
	v_add_f32_e32 v142, s38, v142
	v_add_f32_e32 v142, s42, v142
	v_add_f32_e32 v142, s2, v142
	v_cvt_f32_ubyte1_e32 v169, v40
	v_cvt_f32_ubyte0_e32 v168, v40
	v_pk_fma_f32 v[104:105], s[40:41], v[168:169], v[104:105] op_sel_hi:[0,1,1]
	v_cvt_f32_ubyte1_e32 v171, v44
	v_cvt_f32_ubyte0_e32 v170, v44
	v_pk_fma_f32 v[104:105], s[38:39], v[170:171], v[104:105] op_sel_hi:[0,1,1]
	v_cvt_f32_ubyte1_e32 v169, v48
	v_cvt_f32_ubyte0_e32 v168, v48
	v_pk_fma_f32 v[104:105], s[42:43], v[168:169], v[104:105] op_sel_hi:[0,1,1]
	v_cvt_f32_ubyte1_e32 v171, v52
	v_cvt_f32_ubyte0_e32 v170, v52
	v_pk_fma_f32 v[104:105], s[2:3], v[170:171], v[104:105] op_sel_hi:[0,1,1]
	v_cvt_f32_ubyte3_e32 v169, v40
	v_cvt_f32_ubyte2_e32 v168, v40
	v_pk_fma_f32 v[102:103], s[40:41], v[168:169], v[102:103] op_sel_hi:[0,1,1]
	v_cvt_f32_ubyte3_e32 v171, v44
	v_cvt_f32_ubyte2_e32 v170, v44
	v_pk_fma_f32 v[102:103], s[38:39], v[170:171], v[102:103] op_sel_hi:[0,1,1]
	v_cvt_f32_ubyte3_e32 v169, v48
	v_cvt_f32_ubyte2_e32 v168, v48
	v_pk_fma_f32 v[102:103], s[42:43], v[168:169], v[102:103] op_sel_hi:[0,1,1]
	v_cvt_f32_ubyte3_e32 v171, v52
	v_cvt_f32_ubyte2_e32 v170, v52
	v_pk_fma_f32 v[102:103], s[2:3], v[170:171], v[102:103] op_sel_hi:[0,1,1]
	v_cvt_f32_ubyte1_e32 v169, v41
	v_cvt_f32_ubyte0_e32 v168, v41
	v_pk_fma_f32 v[98:99], s[40:41], v[168:169], v[98:99] op_sel_hi:[0,1,1]
	v_cvt_f32_ubyte1_e32 v171, v45
	v_cvt_f32_ubyte0_e32 v170, v45
	v_pk_fma_f32 v[98:99], s[38:39], v[170:171], v[98:99] op_sel_hi:[0,1,1]
	v_cvt_f32_ubyte1_e32 v169, v49
	v_cvt_f32_ubyte0_e32 v168, v49
	v_pk_fma_f32 v[98:99], s[42:43], v[168:169], v[98:99] op_sel_hi:[0,1,1]
	v_cvt_f32_ubyte1_e32 v171, v53
	v_cvt_f32_ubyte0_e32 v170, v53
	v_pk_fma_f32 v[98:99], s[2:3], v[170:171], v[98:99] op_sel_hi:[0,1,1]
	v_cvt_f32_ubyte3_e32 v169, v41
	v_cvt_f32_ubyte2_e32 v168, v41
	v_pk_fma_f32 v[100:101], s[40:41], v[168:169], v[100:101] op_sel_hi:[0,1,1]
	v_cvt_f32_ubyte3_e32 v171, v45
	v_cvt_f32_ubyte2_e32 v170, v45
	v_pk_fma_f32 v[100:101], s[38:39], v[170:171], v[100:101] op_sel_hi:[0,1,1]
	v_cvt_f32_ubyte3_e32 v169, v49
	v_cvt_f32_ubyte2_e32 v168, v49
	v_pk_fma_f32 v[100:101], s[42:43], v[168:169], v[100:101] op_sel_hi:[0,1,1]
	v_cvt_f32_ubyte3_e32 v171, v53
	v_cvt_f32_ubyte2_e32 v170, v53
	v_pk_fma_f32 v[100:101], s[2:3], v[170:171], v[100:101] op_sel_hi:[0,1,1]
	v_cvt_f32_ubyte1_e32 v169, v42
	v_cvt_f32_ubyte0_e32 v168, v42
	v_pk_fma_f32 v[94:95], s[40:41], v[168:169], v[94:95] op_sel_hi:[0,1,1]
	v_cvt_f32_ubyte1_e32 v171, v46
	v_cvt_f32_ubyte0_e32 v170, v46
	v_pk_fma_f32 v[94:95], s[38:39], v[170:171], v[94:95] op_sel_hi:[0,1,1]
	v_cvt_f32_ubyte1_e32 v169, v50
	v_cvt_f32_ubyte0_e32 v168, v50
	v_pk_fma_f32 v[94:95], s[42:43], v[168:169], v[94:95] op_sel_hi:[0,1,1]
	v_cvt_f32_ubyte1_e32 v171, v54
	v_cvt_f32_ubyte0_e32 v170, v54
	v_pk_fma_f32 v[94:95], s[2:3], v[170:171], v[94:95] op_sel_hi:[0,1,1]
	v_cvt_f32_ubyte3_e32 v169, v42
	v_cvt_f32_ubyte2_e32 v168, v42
	v_pk_fma_f32 v[96:97], s[40:41], v[168:169], v[96:97] op_sel_hi:[0,1,1]
	v_cvt_f32_ubyte3_e32 v171, v46
	v_cvt_f32_ubyte2_e32 v170, v46
	v_pk_fma_f32 v[96:97], s[38:39], v[170:171], v[96:97] op_sel_hi:[0,1,1]
	v_cvt_f32_ubyte3_e32 v169, v50
	v_cvt_f32_ubyte2_e32 v168, v50
	v_pk_fma_f32 v[96:97], s[42:43], v[168:169], v[96:97] op_sel_hi:[0,1,1]
	v_cvt_f32_ubyte3_e32 v171, v54
	v_cvt_f32_ubyte2_e32 v170, v54
	v_pk_fma_f32 v[96:97], s[2:3], v[170:171], v[96:97] op_sel_hi:[0,1,1]
	v_cvt_f32_ubyte1_e32 v169, v43
	v_cvt_f32_ubyte0_e32 v168, v43
	v_pk_fma_f32 v[90:91], s[40:41], v[168:169], v[90:91] op_sel_hi:[0,1,1]
	v_cvt_f32_ubyte1_e32 v171, v47
	v_cvt_f32_ubyte0_e32 v170, v47
	v_pk_fma_f32 v[90:91], s[38:39], v[170:171], v[90:91] op_sel_hi:[0,1,1]
	v_cvt_f32_ubyte1_e32 v169, v51
	v_cvt_f32_ubyte0_e32 v168, v51
	v_pk_fma_f32 v[90:91], s[42:43], v[168:169], v[90:91] op_sel_hi:[0,1,1]
	v_cvt_f32_ubyte1_e32 v171, v55
	v_cvt_f32_ubyte0_e32 v170, v55
	v_pk_fma_f32 v[90:91], s[2:3], v[170:171], v[90:91] op_sel_hi:[0,1,1]
	v_cvt_f32_ubyte3_e32 v169, v43
	v_cvt_f32_ubyte2_e32 v168, v43
	v_pk_fma_f32 v[92:93], s[40:41], v[168:169], v[92:93] op_sel_hi:[0,1,1]
	v_cvt_f32_ubyte3_e32 v171, v47
	v_cvt_f32_ubyte2_e32 v170, v47
	v_pk_fma_f32 v[92:93], s[38:39], v[170:171], v[92:93] op_sel_hi:[0,1,1]
	v_cvt_f32_ubyte3_e32 v169, v51
	v_cvt_f32_ubyte2_e32 v168, v51
	v_pk_fma_f32 v[92:93], s[42:43], v[168:169], v[92:93] op_sel_hi:[0,1,1]
	v_cvt_f32_ubyte3_e32 v171, v55
	v_cvt_f32_ubyte2_e32 v170, v55
	v_pk_fma_f32 v[92:93], s[2:3], v[170:171], v[92:93] op_sel_hi:[0,1,1]
	s_waitcnt vmcnt(10) lgkmcnt(0)
	s_cmp_eq_u32 s80, s33
	s_cbranch_scc1 .Lxp_noswa
	s_lshl_b32 s2, s33, 12
	v_add_u32_e32 v249, s2, v248
	ds_write_b128 v249, v[90:93]
	ds_write_b128 v249, v[94:97] offset:1024
	ds_write_b128 v249, v[98:101] offset:2048
	ds_write_b128 v249, v[102:105] offset:3072
	v_cmp_eq_u32_e32 vcc, s33, v60
	s_nop 1
	v_cndmask_b32_e32 v243, v243, v142, vcc
	s_lshl_b32 s2, s80, 12
	v_add_u32_e32 v249, s2, v248
	ds_read_b128 v[90:93], v249
	ds_read_b128 v[94:97], v249 offset:1024
	ds_read_b128 v[98:101], v249 offset:2048
	ds_read_b128 v[102:105], v249 offset:3072
	s_nop 0
	v_readlane_b32 s2, v243, s80
	v_readlane_b32 s3, v244, s80
	s_nop 1
	v_mov_b32_e32 v142, s2
	v_mov_b32_e32 v137, s3
	s_cmp_eq_u32 s80, 0
	s_cbranch_scc1 .Lxp_lxqa0
	s_cmp_eq_u32 s80, 1
	s_cbranch_scc1 .Lxp_lxqa1
	s_cmp_eq_u32 s80, 2
	s_cbranch_scc1 .Lxp_lxqa2
	v_mov_b32_e32 v133, v236
	v_mov_b32_e32 v134, v237
	v_mov_b32_e32 v135, v238
	v_mov_b32_e32 v136, v239
	s_branch .Lxp_lxqad

.Lxp_syncdb:
	s_and_b32 s84, s84, 0x3fff
	s_lshl_b32 s2, s84, 11
	s_add_u32 s2, s18, s2
	s_addc_u32 s3, s19, 0
	global_load_dwordx4 v[8:11], v252, s[2:3]
	global_load_dwordx4 v[40:43], v252, s[2:3] offset:1024
	s_lshl_b32 s2, s84, 2
	v_writelane_b32 v147, s2, 0
	v_writelane_b32 v0, s85, 0
	s_and_b32 s86, s86, 0x3fff
	s_lshl_b32 s2, s86, 11
	s_add_u32 s2, s18, s2
	s_addc_u32 s3, s19, 0
	global_load_dwordx4 v[16:19], v252, s[2:3]
	global_load_dwordx4 v[44:47], v252, s[2:3] offset:1024
	s_lshl_b32 s2, s86, 2
	v_writelane_b32 v147, s2, 1
	v_writelane_b32 v0, s87, 1
	s_and_b32 s88, s88, 0x3fff
	s_lshl_b32 s2, s88, 11
	s_add_u32 s2, s18, s2
	s_addc_u32 s3, s19, 0
	global_load_dwordx4 v[32:35], v252, s[2:3]
	global_load_dwordx4 v[48:51], v252, s[2:3] offset:1024
	s_lshl_b32 s2, s88, 2
	v_writelane_b32 v147, s2, 2
	v_writelane_b32 v0, s89, 2
	s_and_b32 s90, s90, 0x3fff
	s_lshl_b32 s2, s90, 11
	s_add_u32 s2, s18, s2
	s_addc_u32 s3, s19, 0
	global_load_dwordx4 v[36:39], v252, s[2:3]
	global_load_dwordx4 v[52:55], v252, s[2:3] offset:1024
	s_lshl_b32 s2, s90, 2
	v_writelane_b32 v147, s2, 3
	v_writelane_b32 v0, s91, 3
	global_load_dword v138, v147, s[44:45]
	global_load_dword v139, v147, s[46:47]
	v_dot4_i32_i8 v149, v152, v133, 0
	v_dot4_i32_i8 v150, v156, v133, 0
	v_dot4_i32_i8 v151, v160, v133, 0
	v_dot4_i32_i8 v148, v164, v133, 0
	s_nop 0
	v_dot4c_i32_i8_e32 v149, v153, v134
	v_dot4c_i32_i8_e32 v150, v157, v134
	v_dot4c_i32_i8_e32 v151, v161, v134
	v_dot4c_i32_i8_e32 v148, v165, v134
	v_dot4c_i32_i8_e32 v149, v154, v135
	v_dot4c_i32_i8_e32 v150, v158, v135
	v_dot4c_i32_i8_e32 v151, v162, v135
	v_dot4c_i32_i8_e32 v148, v166, v135
	v_dot4c_i32_i8_e32 v149, v155, v136
	v_dot4c_i32_i8_e32 v150, v159, v136
	v_dot4c_i32_i8_e32 v151, v163, v136
	v_dot4c_i32_i8_e32 v148, v167, v136
	s_add_i32 s3, s25, 3
	s_min_u32 s3, s3, 0x7f
	s_cmp_lt_u32 s3, 64
	s_cselect_b64 vcc, -1, 0
	s_nop 0
	v_cndmask_b32_e32 v249, v241, v240, vcc
	s_nop 1
	v_readlane_b32 s2, v249, s3
	s_and_b32 s3, s2, 31
	s_lshl_b32 s3, s3, 5
	s_bfe_u32 s94, s2, 0x20005
	s_lshl_b32 s2, s94, 11
	s_add_i32 s3, s3, s2
	s_load_dwordx8 s[84:91], s[36:37], s3
	v_cndmask_b32_e64 v143, v149, v150, s[0:1]
	v_cndmask_b32_e64 v144, v150, v149, s[0:1]
	v_cndmask_b32_e64 v145, v151, v148, s[0:1]
	v_cndmask_b32_e64 v146, v148, v151, s[0:1]
	s_nop 1
	v_add_u32_dpp v144, v143, v144 quad_perm:[1,0,3,2] row_mask:0xf bank_mask:0xf
	v_add_u32_dpp v146, v145, v146 quad_perm:[1,0,3,2] row_mask:0xf bank_mask:0xf
	v_cndmask_b32_e64 v143, v144, v146, s[6:7]
	v_cndmask_b32_e64 v145, v146, v144, s[6:7]
	s_nop 1
	v_add_u32_dpp v145, v143, v145 quad_perm:[2,3,0,1] row_mask:0xf bank_mask:0xf
	s_nop 1
	v_add_u32_dpp v145, v145, v145 row_ror:4 row_mask:0xf bank_mask:0xf
	s_nop 1
	v_add_u32_dpp v145, v145, v145 row_ror:8 row_mask:0xf bank_mask:0xf
	ds_bpermute_b32 v143, v126, v145
	s_waitcnt lgkmcnt(0)
	v_add_u32_e32 v145, v145, v143
	ds_bpermute_b32 v143, v127, v145
	s_waitcnt lgkmcnt(0)
	v_add_u32_e32 v145, v145, v143
	v_cvt_f32_i32_e32 v56, v145
	v_mul_f32_e32 v59, v140, v56
	v_mul_f32_e32 v59, v137, v59
	v_mul_f32_e32 v56, 0x3f3504f3, v59
	v_fma_f32 v143, |v56|, s66, v120
	v_fma_f32 v143, |v56|, v143, s67
	v_fma_f32 v143, |v56|, v143, s68
	v_fma_f32 v143, |v56|, v143, s69
	v_fma_f32 v143, |v56|, v143, s70
	v_fma_f32 v143, |v56|, v143, s71
	v_fma_f32 v143, |v56|, v143, |v56|
	v_mul_f32_e32 v144, 0xbfb8aa3b, v143
	v_fma_f32 v146, v143, s72, -v144
	v_rndne_f32_e32 v3, v144
	v_fmac_f32_e32 v146, 0xb2a5705f, v143
	v_sub_f32_e32 v144, v144, v3
	v_add_f32_e32 v144, v144, v146
	v_cvt_i32_f32_e32 v146, v3
	v_exp_f32_e32 v144, v144
	v_cmp_nlt_f32_e32 vcc, s73, v143
	v_ldexp_f32 v144, v144, v146
	s_nop 0
	v_cndmask_b32_e32 v144, 0, v144, vcc
	v_cmp_ngt_f32_e32 vcc, s74, v143
	s_nop 1
	v_cndmask_b32_e32 v143, v121, v144, vcc
	v_sub_f32_e32 v143, 1.0, v143
	v_mul_f32_e32 v168, v56, v56
	v_fmamk_f32 v169, v168, 0xba1345e1, v117
	v_fmaak_f32 v169, v168, v169, 0xbcdac9b8
	v_fmaak_f32 v169, v168, v169, 0x3de703be
	v_fmaak_f32 v169, v168, v169, 0xbec09330
	v_fmaak_f32 v168, v168, v169, 0x3e0375d0
	v_fma_f32 v168, |v56|, v168, |v56|
	v_cmp_nlt_f32_e64 vcc, |v56|, 1.0
	s_nop 1
	v_cndmask_b32_e32 v143, v168, v143, vcc
	v_bfi_b32 v146, s75, v143, v56
	v_fma_f32 v145, v59, v146, v59
	v_mul_f32_e32 v144, v1, v145
	v_mul_f32_e32 v143, v141, v144
	s_nop 1
	v_readlane_b32 s40, v143, 0
	v_readlane_b32 s38, v143, 1
	v_readlane_b32 s42, v143, 2
	v_readlane_b32 s2, v143, 3
	s_nop 1
	v_add_f32_e32 v142, s40, v142
	v_add_f32_e32 v142, s38, v142
	v_add_f32_e32 v142, s42, v142
	v_add_f32_e32 v142, s2, v142
	v_cvt_f32_ubyte1_e32 v169, v12
	v_cvt_f32_ubyte0_e32 v168, v12
	v_pk_fma_f32 v[104:105], s[40:41], v[168:169], v[104:105] op_sel_hi:[0,1,1]
	v_cvt_f32_ubyte1_e32 v171, v20
	v_cvt_f32_ubyte0_e32 v170, v20
	v_pk_fma_f32 v[104:105], s[38:39], v[170:171], v[104:105] op_sel_hi:[0,1,1]
	v_cvt_f32_ubyte1_e32 v169, v24
	v_cvt_f32_ubyte0_e32 v168, v24
	v_pk_fma_f32 v[104:105], s[42:43], v[168:169], v[104:105] op_sel_hi:[0,1,1]
	v_cvt_f32_ubyte1_e32 v171, v28
	v_cvt_f32_ubyte0_e32 v170, v28
	v_pk_fma_f32 v[104:105], s[2:3], v[170:171], v[104:105] op_sel_hi:[0,1,1]
	v_cvt_f32_ubyte3_e32 v169, v12
	v_cvt_f32_ubyte2_e32 v168, v12
	v_pk_fma_f32 v[102:103], s[40:41], v[168:169], v[102:103] op_sel_hi:[0,1,1]
	v_cvt_f32_ubyte3_e32 v171, v20
	v_cvt_f32_ubyte2_e32 v170, v20
	v_pk_fma_f32 v[102:103], s[38:39], v[170:171], v[102:103] op_sel_hi:[0,1,1]
	v_cvt_f32_ubyte3_e32 v169, v24
	v_cvt_f32_ubyte2_e32 v168, v24
	v_pk_fma_f32 v[102:103], s[42:43], v[168:169], v[102:103] op_sel_hi:[0,1,1]
	v_cvt_f32_ubyte3_e32 v171, v28
	v_cvt_f32_ubyte2_e32 v170, v28
	v_pk_fma_f32 v[102:103], s[2:3], v[170:171], v[102:103] op_sel_hi:[0,1,1]
	v_cvt_f32_ubyte1_e32 v169, v13
	v_cvt_f32_ubyte0_e32 v168, v13
	v_pk_fma_f32 v[98:99], s[40:41], v[168:169], v[98:99] op_sel_hi:[0,1,1]
	v_cvt_f32_ubyte1_e32 v171, v21
	v_cvt_f32_ubyte0_e32 v170, v21
	v_pk_fma_f32 v[98:99], s[38:39], v[170:171], v[98:99] op_sel_hi:[0,1,1]
	v_cvt_f32_ubyte1_e32 v169, v25
	v_cvt_f32_ubyte0_e32 v168, v25
	v_pk_fma_f32 v[98:99], s[42:43], v[168:169], v[98:99] op_sel_hi:[0,1,1]
	v_cvt_f32_ubyte1_e32 v171, v29
	v_cvt_f32_ubyte0_e32 v170, v29
	v_pk_fma_f32 v[98:99], s[2:3], v[170:171], v[98:99] op_sel_hi:[0,1,1]
	v_cvt_f32_ubyte3_e32 v169, v13
	v_cvt_f32_ubyte2_e32 v168, v13
	v_pk_fma_f32 v[100:101], s[40:41], v[168:169], v[100:101] op_sel_hi:[0,1,1]
	v_cvt_f32_ubyte3_e32 v171, v21
	v_cvt_f32_ubyte2_e32 v170, v21
	v_pk_fma_f32 v[100:101], s[38:39], v[170:171], v[100:101] op_sel_hi:[0,1,1]
	v_cvt_f32_ubyte3_e32 v169, v25
	v_cvt_f32_ubyte2_e32 v168, v25
	v_pk_fma_f32 v[100:101], s[42:43], v[168:169], v[100:101] op_sel_hi:[0,1,1]
	v_cvt_f32_ubyte3_e32 v171, v29
	v_cvt_f32_ubyte2_e32 v170, v29
	v_pk_fma_f32 v[100:101], s[2:3], v[170:171], v[100:101] op_sel_hi:[0,1,1]
	v_cvt_f32_ubyte1_e32 v169, v14
	v_cvt_f32_ubyte0_e32 v168, v14
	v_pk_fma_f32 v[94:95], s[40:41], v[168:169], v[94:95] op_sel_hi:[0,1,1]
	v_cvt_f32_ubyte1_e32 v171, v22
	v_cvt_f32_ubyte0_e32 v170, v22
	v_pk_fma_f32 v[94:95], s[38:39], v[170:171], v[94:95] op_sel_hi:[0,1,1]
	v_cvt_f32_ubyte1_e32 v169, v26
	v_cvt_f32_ubyte0_e32 v168, v26
	v_pk_fma_f32 v[94:95], s[42:43], v[168:169], v[94:95] op_sel_hi:[0,1,1]
	v_cvt_f32_ubyte1_e32 v171, v30
	v_cvt_f32_ubyte0_e32 v170, v30
	v_pk_fma_f32 v[94:95], s[2:3], v[170:171], v[94:95] op_sel_hi:[0,1,1]
	v_cvt_f32_ubyte3_e32 v169, v14
	v_cvt_f32_ubyte2_e32 v168, v14
	v_pk_fma_f32 v[96:97], s[40:41], v[168:169], v[96:97] op_sel_hi:[0,1,1]
	v_cvt_f32_ubyte3_e32 v171, v22
	v_cvt_f32_ubyte2_e32 v170, v22
	v_pk_fma_f32 v[96:97], s[38:39], v[170:171], v[96:97] op_sel_hi:[0,1,1]
	v_cvt_f32_ubyte3_e32 v169, v26
	v_cvt_f32_ubyte2_e32 v168, v26
	v_pk_fma_f32 v[96:97], s[42:43], v[168:169], v[96:97] op_sel_hi:[0,1,1]
	v_cvt_f32_ubyte3_e32 v171, v30
	v_cvt_f32_ubyte2_e32 v170, v30
	v_pk_fma_f32 v[96:97], s[2:3], v[170:171], v[96:97] op_sel_hi:[0,1,1]
	v_cvt_f32_ubyte1_e32 v169, v15
	v_cvt_f32_ubyte0_e32 v168, v15
	v_pk_fma_f32 v[90:91], s[40:41], v[168:169], v[90:91] op_sel_hi:[0,1,1]
	v_cvt_f32_ubyte1_e32 v171, v23
	v_cvt_f32_ubyte0_e32 v170, v23
	v_pk_fma_f32 v[90:91], s[38:39], v[170:171], v[90:91] op_sel_hi:[0,1,1]
	v_cvt_f32_ubyte1_e32 v169, v27
	v_cvt_f32_ubyte0_e32 v168, v27
	v_pk_fma_f32 v[90:91], s[42:43], v[168:169], v[90:91] op_sel_hi:[0,1,1]
	v_cvt_f32_ubyte1_e32 v171, v31
	v_cvt_f32_ubyte0_e32 v170, v31
	v_pk_fma_f32 v[90:91], s[2:3], v[170:171], v[90:91] op_sel_hi:[0,1,1]
	v_cvt_f32_ubyte3_e32 v169, v15
	v_cvt_f32_ubyte2_e32 v168, v15
	v_pk_fma_f32 v[92:93], s[40:41], v[168:169], v[92:93] op_sel_hi:[0,1,1]
	v_cvt_f32_ubyte3_e32 v171, v23
	v_cvt_f32_ubyte2_e32 v170, v23
	v_pk_fma_f32 v[92:93], s[38:39], v[170:171], v[92:93] op_sel_hi:[0,1,1]
	v_cvt_f32_ubyte3_e32 v169, v27
	v_cvt_f32_ubyte2_e32 v168, v27
	v_pk_fma_f32 v[92:93], s[42:43], v[168:169], v[92:93] op_sel_hi:[0,1,1]
	v_cvt_f32_ubyte3_e32 v171, v31
	v_cvt_f32_ubyte2_e32 v170, v31
	v_pk_fma_f32 v[92:93], s[2:3], v[170:171], v[92:93] op_sel_hi:[0,1,1]
	s_waitcnt vmcnt(10) lgkmcnt(0)
	s_cmp_eq_u32 s80, s33
	s_cbranch_scc1 .Lxp_noswb
	s_lshl_b32 s2, s33, 12
	v_add_u32_e32 v249, s2, v248
	ds_write_b128 v249, v[90:93]
	ds_write_b128 v249, v[94:97] offset:1024
	ds_write_b128 v249, v[98:101] offset:2048
	ds_write_b128 v249, v[102:105] offset:3072
	v_cmp_eq_u32_e32 vcc, s33, v60
	s_nop 1
	v_cndmask_b32_e32 v243, v243, v142, vcc
	s_lshl_b32 s2, s80, 12
	v_add_u32_e32 v249, s2, v248
	ds_read_b128 v[90:93], v249
	ds_read_b128 v[94:97], v249 offset:1024
	ds_read_b128 v[98:101], v249 offset:2048
	ds_read_b128 v[102:105], v249 offset:3072
	s_nop 0
	v_readlane_b32 s2, v243, s80
	v_readlane_b32 s3, v244, s80
	s_nop 1
	v_mov_b32_e32 v142, s2
	v_mov_b32_e32 v137, s3
	s_cmp_eq_u32 s80, 0
	s_cbranch_scc1 .Lxp_lxqb0
	s_cmp_eq_u32 s80, 1
	s_cbranch_scc1 .Lxp_lxqb1
	s_cmp_eq_u32 s80, 2
	s_cbranch_scc1 .Lxp_lxqb2
	v_mov_b32_e32 v133, v236
	v_mov_b32_e32 v134, v237
	v_mov_b32_e32 v135, v238
	v_mov_b32_e32 v136, v239
	s_branch .Lxp_lxqbd

.Lxp_syncdc:
	s_and_b32 s84, s84, 0x3fff
	s_lshl_b32 s2, s84, 11
	s_add_u32 s2, s18, s2
	s_addc_u32 s3, s19, 0
	global_load_dwordx4 v[152:155], v252, s[2:3]
	global_load_dwordx4 v[12:15], v252, s[2:3] offset:1024
	s_lshl_b32 s2, s84, 2
	v_writelane_b32 v147, s2, 0
	v_writelane_b32 v1, s85, 0
	s_and_b32 s86, s86, 0x3fff
	s_lshl_b32 s2, s86, 11
	s_add_u32 s2, s18, s2
	s_addc_u32 s3, s19, 0
	global_load_dwordx4 v[156:159], v252, s[2:3]
	global_load_dwordx4 v[20:23], v252, s[2:3] offset:1024
	s_lshl_b32 s2, s86, 2
	v_writelane_b32 v147, s2, 1
	v_writelane_b32 v1, s87, 1
	s_and_b32 s88, s88, 0x3fff
	s_lshl_b32 s2, s88, 11
	s_add_u32 s2, s18, s2
	s_addc_u32 s3, s19, 0
	global_load_dwordx4 v[160:163], v252, s[2:3]
	global_load_dwordx4 v[24:27], v252, s[2:3] offset:1024
	s_lshl_b32 s2, s88, 2
	v_writelane_b32 v147, s2, 2
	v_writelane_b32 v1, s89, 2
	s_and_b32 s90, s90, 0x3fff
	s_lshl_b32 s2, s90, 11
	s_add_u32 s2, s18, s2
	s_addc_u32 s3, s19, 0
	global_load_dwordx4 v[164:167], v252, s[2:3]
	global_load_dwordx4 v[28:31], v252, s[2:3] offset:1024
	s_lshl_b32 s2, s90, 2
	v_writelane_b32 v147, s2, 3
	v_writelane_b32 v1, s91, 3
	global_load_dword v140, v147, s[44:45]
	global_load_dword v141, v147, s[46:47]
	v_dot4_i32_i8 v149, v72, v133, 0
	v_dot4_i32_i8 v150, v76, v133, 0
	v_dot4_i32_i8 v151, v80, v133, 0
	v_dot4_i32_i8 v148, v84, v133, 0
	s_nop 0
	v_dot4c_i32_i8_e32 v149, v73, v134
	v_dot4c_i32_i8_e32 v150, v77, v134
	v_dot4c_i32_i8_e32 v151, v81, v134
	v_dot4c_i32_i8_e32 v148, v85, v134
	v_dot4c_i32_i8_e32 v149, v74, v135
	v_dot4c_i32_i8_e32 v150, v78, v135
	v_dot4c_i32_i8_e32 v151, v82, v135
	v_dot4c_i32_i8_e32 v148, v86, v135
	v_dot4c_i32_i8_e32 v149, v75, v136
	v_dot4c_i32_i8_e32 v150, v79, v136
	v_dot4c_i32_i8_e32 v151, v83, v136
	v_dot4c_i32_i8_e32 v148, v87, v136
	s_add_i32 s3, s25, 3
	s_min_u32 s3, s3, 0x7f
	s_cmp_lt_u32 s3, 64
	s_cselect_b64 vcc, -1, 0
	s_nop 0
	v_cndmask_b32_e32 v249, v241, v240, vcc
	s_nop 1
	v_readlane_b32 s2, v249, s3
	s_and_b32 s3, s2, 31
	s_lshl_b32 s3, s3, 5
	s_bfe_u32 s94, s2, 0x20005
	s_lshl_b32 s2, s94, 11
	s_add_i32 s3, s3, s2
	s_load_dwordx8 s[84:91], s[36:37], s3
	v_cndmask_b32_e64 v143, v149, v150, s[0:1]
	v_cndmask_b32_e64 v144, v150, v149, s[0:1]
	v_cndmask_b32_e64 v145, v151, v148, s[0:1]
	v_cndmask_b32_e64 v146, v148, v151, s[0:1]
	s_nop 1
	v_add_u32_dpp v144, v143, v144 quad_perm:[1,0,3,2] row_mask:0xf bank_mask:0xf
	v_add_u32_dpp v146, v145, v146 quad_perm:[1,0,3,2] row_mask:0xf bank_mask:0xf
	v_cndmask_b32_e64 v143, v144, v146, s[6:7]
	v_cndmask_b32_e64 v145, v146, v144, s[6:7]
	s_nop 1
	v_add_u32_dpp v145, v143, v145 quad_perm:[2,3,0,1] row_mask:0xf bank_mask:0xf
	s_nop 1
	v_add_u32_dpp v145, v145, v145 row_ror:4 row_mask:0xf bank_mask:0xf
	s_nop 1
	v_add_u32_dpp v145, v145, v145 row_ror:8 row_mask:0xf bank_mask:0xf
	ds_bpermute_b32 v143, v126, v145
	s_waitcnt lgkmcnt(0)
	v_add_u32_e32 v145, v145, v143
	ds_bpermute_b32 v143, v127, v145
	s_waitcnt lgkmcnt(0)
	v_add_u32_e32 v145, v145, v143
	v_cvt_f32_i32_e32 v56, v145
	v_mul_f32_e32 v59, v88, v56
	v_mul_f32_e32 v59, v137, v59
	v_mul_f32_e32 v56, 0x3f3504f3, v59
	v_fma_f32 v143, |v56|, s66, v120
	v_fma_f32 v143, |v56|, v143, s67
	v_fma_f32 v143, |v56|, v143, s68
	v_fma_f32 v143, |v56|, v143, s69
	v_fma_f32 v143, |v56|, v143, s70
	v_fma_f32 v143, |v56|, v143, s71
	v_fma_f32 v143, |v56|, v143, |v56|
	v_mul_f32_e32 v144, 0xbfb8aa3b, v143
	v_fma_f32 v146, v143, s72, -v144
	v_rndne_f32_e32 v3, v144
	v_fmac_f32_e32 v146, 0xb2a5705f, v143
	v_sub_f32_e32 v144, v144, v3
	v_add_f32_e32 v144, v144, v146
	v_cvt_i32_f32_e32 v146, v3
	v_exp_f32_e32 v144, v144
	v_cmp_nlt_f32_e32 vcc, s73, v143
	v_ldexp_f32 v144, v144, v146
	s_nop 0
	v_cndmask_b32_e32 v144, 0, v144, vcc
	v_cmp_ngt_f32_e32 vcc, s74, v143
	s_nop 1
	v_cndmask_b32_e32 v143, v121, v144, vcc
	v_sub_f32_e32 v143, 1.0, v143
	v_mul_f32_e32 v168, v56, v56
	v_fmamk_f32 v169, v168, 0xba1345e1, v117
	v_fmaak_f32 v169, v168, v169, 0xbcdac9b8
	v_fmaak_f32 v169, v168, v169, 0x3de703be
	v_fmaak_f32 v169, v168, v169, 0xbec09330
	v_fmaak_f32 v168, v168, v169, 0x3e0375d0
	v_fma_f32 v168, |v56|, v168, |v56|
	v_cmp_nlt_f32_e64 vcc, |v56|, 1.0
	s_nop 1
	v_cndmask_b32_e32 v143, v168, v143, vcc
	v_bfi_b32 v146, s75, v143, v56
	v_fma_f32 v145, v59, v146, v59
	v_mul_f32_e32 v144, v2, v145
	v_mul_f32_e32 v143, v89, v144
	s_nop 1
	v_readlane_b32 s40, v143, 0
	v_readlane_b32 s38, v143, 1
	v_readlane_b32 s42, v143, 2
	v_readlane_b32 s2, v143, 3
	s_nop 1
	v_add_f32_e32 v142, s40, v142
	v_add_f32_e32 v142, s38, v142
	v_add_f32_e32 v142, s42, v142
	v_add_f32_e32 v142, s2, v142
	v_cvt_f32_ubyte1_e32 v169, v64
	v_cvt_f32_ubyte0_e32 v168, v64
	v_pk_fma_f32 v[104:105], s[40:41], v[168:169], v[104:105] op_sel_hi:[0,1,1]
	v_cvt_f32_ubyte1_e32 v171, v68
	v_cvt_f32_ubyte0_e32 v170, v68
	v_pk_fma_f32 v[104:105], s[38:39], v[170:171], v[104:105] op_sel_hi:[0,1,1]
	v_cvt_f32_ubyte1_e32 v169, v4
	v_cvt_f32_ubyte0_e32 v168, v4
	v_pk_fma_f32 v[104:105], s[42:43], v[168:169], v[104:105] op_sel_hi:[0,1,1]
	v_cvt_f32_ubyte1_e32 v171, v128
	v_cvt_f32_ubyte0_e32 v170, v128
	v_pk_fma_f32 v[104:105], s[2:3], v[170:171], v[104:105] op_sel_hi:[0,1,1]
	v_cvt_f32_ubyte3_e32 v169, v64
	v_cvt_f32_ubyte2_e32 v168, v64
	v_pk_fma_f32 v[102:103], s[40:41], v[168:169], v[102:103] op_sel_hi:[0,1,1]
	v_cvt_f32_ubyte3_e32 v171, v68
	v_cvt_f32_ubyte2_e32 v170, v68
	v_pk_fma_f32 v[102:103], s[38:39], v[170:171], v[102:103] op_sel_hi:[0,1,1]
	v_cvt_f32_ubyte3_e32 v169, v4
	v_cvt_f32_ubyte2_e32 v168, v4
	v_pk_fma_f32 v[102:103], s[42:43], v[168:169], v[102:103] op_sel_hi:[0,1,1]
	v_cvt_f32_ubyte3_e32 v171, v128
	v_cvt_f32_ubyte2_e32 v170, v128
	v_pk_fma_f32 v[102:103], s[2:3], v[170:171], v[102:103] op_sel_hi:[0,1,1]
	v_cvt_f32_ubyte1_e32 v169, v65
	v_cvt_f32_ubyte0_e32 v168, v65
	v_pk_fma_f32 v[98:99], s[40:41], v[168:169], v[98:99] op_sel_hi:[0,1,1]
	v_cvt_f32_ubyte1_e32 v171, v69
	v_cvt_f32_ubyte0_e32 v170, v69
	v_pk_fma_f32 v[98:99], s[38:39], v[170:171], v[98:99] op_sel_hi:[0,1,1]
	v_cvt_f32_ubyte1_e32 v169, v5
	v_cvt_f32_ubyte0_e32 v168, v5
	v_pk_fma_f32 v[98:99], s[42:43], v[168:169], v[98:99] op_sel_hi:[0,1,1]
	v_cvt_f32_ubyte1_e32 v171, v129
	v_cvt_f32_ubyte0_e32 v170, v129
	v_pk_fma_f32 v[98:99], s[2:3], v[170:171], v[98:99] op_sel_hi:[0,1,1]
	v_cvt_f32_ubyte3_e32 v169, v65
	v_cvt_f32_ubyte2_e32 v168, v65
	v_pk_fma_f32 v[100:101], s[40:41], v[168:169], v[100:101] op_sel_hi:[0,1,1]
	v_cvt_f32_ubyte3_e32 v171, v69
	v_cvt_f32_ubyte2_e32 v170, v69
	v_pk_fma_f32 v[100:101], s[38:39], v[170:171], v[100:101] op_sel_hi:[0,1,1]
	v_cvt_f32_ubyte3_e32 v169, v5
	v_cvt_f32_ubyte2_e32 v168, v5
	v_pk_fma_f32 v[100:101], s[42:43], v[168:169], v[100:101] op_sel_hi:[0,1,1]
	v_cvt_f32_ubyte3_e32 v171, v129
	v_cvt_f32_ubyte2_e32 v170, v129
	v_pk_fma_f32 v[100:101], s[2:3], v[170:171], v[100:101] op_sel_hi:[0,1,1]
	v_cvt_f32_ubyte1_e32 v169, v66
	v_cvt_f32_ubyte0_e32 v168, v66
	v_pk_fma_f32 v[94:95], s[40:41], v[168:169], v[94:95] op_sel_hi:[0,1,1]
	v_cvt_f32_ubyte1_e32 v171, v70
	v_cvt_f32_ubyte0_e32 v170, v70
	v_pk_fma_f32 v[94:95], s[38:39], v[170:171], v[94:95] op_sel_hi:[0,1,1]
	v_cvt_f32_ubyte1_e32 v169, v6
	v_cvt_f32_ubyte0_e32 v168, v6
	v_pk_fma_f32 v[94:95], s[42:43], v[168:169], v[94:95] op_sel_hi:[0,1,1]
	v_cvt_f32_ubyte1_e32 v171, v130
	v_cvt_f32_ubyte0_e32 v170, v130
	v_pk_fma_f32 v[94:95], s[2:3], v[170:171], v[94:95] op_sel_hi:[0,1,1]
	v_cvt_f32_ubyte3_e32 v169, v66
	v_cvt_f32_ubyte2_e32 v168, v66
	v_pk_fma_f32 v[96:97], s[40:41], v[168:169], v[96:97] op_sel_hi:[0,1,1]
	v_cvt_f32_ubyte3_e32 v171, v70
	v_cvt_f32_ubyte2_e32 v170, v70
	v_pk_fma_f32 v[96:97], s[38:39], v[170:171], v[96:97] op_sel_hi:[0,1,1]
	v_cvt_f32_ubyte3_e32 v169, v6
	v_cvt_f32_ubyte2_e32 v168, v6
	v_pk_fma_f32 v[96:97], s[42:43], v[168:169], v[96:97] op_sel_hi:[0,1,1]
	v_cvt_f32_ubyte3_e32 v171, v130
	v_cvt_f32_ubyte2_e32 v170, v130
	v_pk_fma_f32 v[96:97], s[2:3], v[170:171], v[96:97] op_sel_hi:[0,1,1]
	v_cvt_f32_ubyte1_e32 v169, v67
	v_cvt_f32_ubyte0_e32 v168, v67
	v_pk_fma_f32 v[90:91], s[40:41], v[168:169], v[90:91] op_sel_hi:[0,1,1]
	v_cvt_f32_ubyte1_e32 v171, v71
	v_cvt_f32_ubyte0_e32 v170, v71
	v_pk_fma_f32 v[90:91], s[38:39], v[170:171], v[90:91] op_sel_hi:[0,1,1]
	v_cvt_f32_ubyte1_e32 v169, v7
	v_cvt_f32_ubyte0_e32 v168, v7
	v_pk_fma_f32 v[90:91], s[42:43], v[168:169], v[90:91] op_sel_hi:[0,1,1]
	v_cvt_f32_ubyte1_e32 v171, v131
	v_cvt_f32_ubyte0_e32 v170, v131
	v_pk_fma_f32 v[90:91], s[2:3], v[170:171], v[90:91] op_sel_hi:[0,1,1]
	v_cvt_f32_ubyte3_e32 v169, v67
	v_cvt_f32_ubyte2_e32 v168, v67
	v_pk_fma_f32 v[92:93], s[40:41], v[168:169], v[92:93] op_sel_hi:[0,1,1]
	v_cvt_f32_ubyte3_e32 v171, v71
	v_cvt_f32_ubyte2_e32 v170, v71
	v_pk_fma_f32 v[92:93], s[38:39], v[170:171], v[92:93] op_sel_hi:[0,1,1]
	v_cvt_f32_ubyte3_e32 v169, v7
	v_cvt_f32_ubyte2_e32 v168, v7
	v_pk_fma_f32 v[92:93], s[42:43], v[168:169], v[92:93] op_sel_hi:[0,1,1]
	v_cvt_f32_ubyte3_e32 v171, v131
	v_cvt_f32_ubyte2_e32 v170, v131
	v_pk_fma_f32 v[92:93], s[2:3], v[170:171], v[92:93] op_sel_hi:[0,1,1]
	s_waitcnt vmcnt(10) lgkmcnt(0)
	s_cmp_eq_u32 s80, s33
	s_cbranch_scc1 .Lxp_noswc
	s_lshl_b32 s2, s33, 12
	v_add_u32_e32 v249, s2, v248
	ds_write_b128 v249, v[90:93]
	ds_write_b128 v249, v[94:97] offset:1024
	ds_write_b128 v249, v[98:101] offset:2048
	ds_write_b128 v249, v[102:105] offset:3072
	v_cmp_eq_u32_e32 vcc, s33, v60
	s_nop 1
	v_cndmask_b32_e32 v243, v243, v142, vcc
	s_lshl_b32 s2, s80, 12
	v_add_u32_e32 v249, s2, v248
	ds_read_b128 v[90:93], v249
	ds_read_b128 v[94:97], v249 offset:1024
	ds_read_b128 v[98:101], v249 offset:2048
	ds_read_b128 v[102:105], v249 offset:3072
	s_nop 0
	v_readlane_b32 s2, v243, s80
	v_readlane_b32 s3, v244, s80
	s_nop 1
	v_mov_b32_e32 v142, s2
	v_mov_b32_e32 v137, s3
	s_cmp_eq_u32 s80, 0
	s_cbranch_scc1 .Lxp_lxqc0
	s_cmp_eq_u32 s80, 1
	s_cbranch_scc1 .Lxp_lxqc1
	s_cmp_eq_u32 s80, 2
	s_cbranch_scc1 .Lxp_lxqc2
	v_mov_b32_e32 v133, v236
	v_mov_b32_e32 v134, v237
	v_mov_b32_e32 v135, v238
	v_mov_b32_e32 v136, v239
	s_branch .Lxp_lxqcd
